# rwkv_post tasks remapped to the owner group; group barrier at rwkv_post->out-proj
# speedup vs baseline: 1.0163x; 1.0029x over previous
.LBB0_1227:
	v_readlane_b32 s16, v250, 0
	v_readlane_b32 s18, v250, 2
	v_readlane_b32 s19, v250, 3
	s_cmp_le_i32 s18, s0
	s_cselect_b64 s[2:3], -1, 0
	s_cmp_lt_i32 s0, s19
	s_cselect_b64 s[8:9], -1, 0
	v_readlane_b32 s17, v250, 1
	s_and_b64 s[2:3], s[2:3], s[8:9]
	s_mov_b64 s[16:17], 0
	s_andn2_b64 vcc, exec, s[2:3]
	s_mov_b64 s[72:73], 0
	s_cbranch_vccnz .LBB0_1299
	s_mov_b32 s10, s80
	s_mov_b32 s0, -1
	s_add_i32 s34, s10, s67
	s_mov_b32 s98, s81
	s_mov_b32 s99, 0x20000
	s_cmp_lg_u32 s94, 0x100
	s_cbranch_scc1 .Lmy_postmap
	v_readlane_b32 s99, v250, 7
	s_and_b32 s98, s99, 7
	s_lshl_b32 s98, s98, 3
	s_bfe_u32 s34, s99, 0x30003
	s_or_b32 s98, s98, s34
	s_lshl_b32 s98, s98, 2
	s_lshr_b32 s99, s99, 6
	s_or_b32 s99, s99, s98
	s_lshl_b32 s34, s99, 9
	s_add_i32 s99, s34, 0x200
	s_add_i32 s34, s34, s10
	s_movk_i32 s98, 8
.Lmy_postmap:
	s_waitcnt lgkmcnt(0)
	v_mbcnt_lo_u32_b32 v0, s0, 0
	v_mbcnt_hi_u32_b32 v0, s0, v0
	s_mov_b64 s[28:29], s[96:97]
	s_mov_b64 s[26:27], s[96:97]
	s_mov_b64 s[20:21], s[96:97]
	s_mov_b64 s[18:19], s[96:97]
	s_mov_b64 s[8:9], s[96:97]
	s_mov_b64 s[12:13], s[96:97]
	s_mov_b64 s[22:23], s[96:97]
	s_cmp_ge_i32 s34, s99
	s_cbranch_scc1 .LBB0_1243
	s_load_dwordx2 s[2:3], s[28:29], 0x110
	s_nop 0
	s_load_dwordx2 s[26:27], s[26:27], 0x110
	s_nop 0
	s_load_dwordx2 s[20:21], s[20:21], 0x110
	s_nop 0
	s_load_dwordx2 s[28:29], s[18:19], 0x110
	s_load_dwordx2 s[30:31], s[22:23], 0x110
	s_waitcnt lgkmcnt(0)
	s_add_u32 s18, s2, 0x49300000
	s_addc_u32 s19, s3, 0
	s_add_u32 s0, s26, 0x43b00000
	s_addc_u32 s2, s27, 0
	s_add_u32 s3, s20, 0x47b00000
	s_addc_u32 s7, s21, 0
	s_add_u32 s28, s28, 0x51300000
	s_load_dwordx2 s[20:21], s[8:9], 0xc0
	s_load_dwordx2 s[22:23], s[12:13], 0xc8
	s_addc_u32 s29, s29, 0
	v_readlane_b32 s8, v253, 45
	s_add_u32 s30, s30, s8
	s_addc_u32 s31, s31, 0
	v_ashrrev_i32_e32 v49, 4, v0
	v_lshlrev_b32_e32 v0, 2, v0
	s_lshl_b32 s8, s10, 2
	v_readlane_b32 s9, v252, 28
	v_mov_b32_e32 v50, 0
	v_mov_b32_e32 v4, 0
	v_and_b32_e32 v48, 60, v0
	s_add_i32 s33, s9, s8
	v_mov_b32_e32 v5, v4
	v_mov_b32_e32 v6, v4
	v_mov_b32_e32 v7, v4
	v_mov_b32_e32 v8, v4
	v_mov_b32_e32 v9, v4
	v_mov_b32_e32 v10, v4
	v_mov_b32_e32 v11, v4
	v_mov_b32_e32 v12, v4
	v_mov_b32_e32 v13, v4
	v_mov_b32_e32 v14, v4
	v_mov_b32_e32 v15, v4
	v_mov_b32_e32 v51, v50
	v_mov_b32_e32 v58, v50
	v_mov_b32_e32 v59, v50
	v_mov_b32_e32 v60, v50
	v_mov_b32_e32 v61, v50
	v_mov_b32_e32 v62, v50
	v_mov_b32_e32 v63, v50
	v_mov_b32_e32 v64, v50
	v_mov_b32_e32 v65, v50
	v_mov_b32_e32 v66, v50
	v_mov_b32_e32 v67, v50
	s_branch .LBB0_1231
.LBB0_1230:
	s_add_i32 s8, s36, s98
	s_add_i32 s8, s8, s98
	s_add_i32 s34, s8, s98
	s_add_i32 s33, s33, s86
	s_cmp_lt_i32 s34, s99
	s_cbranch_scc0 .LBB0_1243
.LBB0_1231:
	s_and_b32 s9, s33, 28
	v_add_u32_e32 v76, s9, v49
	s_ashr_i32 s9, s34, 11
	s_andn2_b32 s9, s9, 31
	s_ashr_i32 s8, s34, 3
	v_add_u32_e32 v0, s9, v76
	v_ashrrev_i32_e32 v1, 31, v0
	s_lshl_b32 s9, s8, 7
	v_lshlrev_b64 v[0:1], 20, v[0:1]
	s_and_b32 s10, s9, 0xfff80
	s_ashr_i32 s9, s8, 31
	v_lshl_or_b32 v68, v76, 6, v48
	v_lshl_add_u64 v[0:1], s[18:19], 0, v[0:1]
	s_lshl_b64 s[12:13], s[8:9], 12
	v_lshl_add_u64 v[0:1], v[0:1], 0, s[10:11]
	v_lshlrev_b32_e32 v224, 1, v48
	s_add_u32 s26, s0, s12
	v_ashrrev_i32_e32 v69, 31, v68
	v_lshl_add_u64 v[0:1], v[0:1], 0, v[224:225]
	s_addc_u32 s27, s2, s13
	v_lshlrev_b64 v[78:79], 1, v[68:69]
	global_load_dwordx2 v[80:81], v[0:1], off
	v_lshl_add_u64 v[0:1], s[26:27], 0, v[78:79]
	s_add_u32 s26, s28, s12
	s_addc_u32 s27, s29, s13
	s_lshl_b64 s[8:9], s[8:9], 7
	s_add_u32 s8, s3, s8
	v_lshlrev_b64 v[2:3], 2, v[68:69]
	global_load_dwordx2 v[72:73], v[0:1], off
	v_lshl_add_u64 v[0:1], s[26:27], 0, v[78:79]
	v_ashrrev_i32_e32 v77, 31, v76
	s_addc_u32 s9, s7, s9
	s_waitcnt lgkmcnt(0)
	v_lshl_add_u64 v[40:41], s[20:21], 0, v[2:3]
	v_lshl_add_u64 v[2:3], s[22:23], 0, v[2:3]
	global_load_dwordx2 v[70:71], v[0:1], off
	v_lshl_add_u64 v[0:1], v[76:77], 2, s[8:9]
	global_load_dwordx4 v[40:43], v[40:41], off
	s_nop 0
	global_load_dwordx4 v[44:47], v[2:3], off
	global_load_dword v74, v[0:1], off
	s_add_i32 s36, s34, s98
	s_cmp_lt_i32 s36, s99
	s_cselect_b64 s[26:27], -1, 0
	s_cmp_ge_i32 s36, s99
	s_waitcnt vmcnt(0)
	v_cvt_f32_f16_e32 v0, v80
	v_cvt_f32_f16_e32 v2, v81
	v_cvt_f32_f16_sdwa v3, v81 dst_sel:DWORD dst_unused:UNUSED_PAD src0_sel:WORD_1
	v_cvt_f32_f16_sdwa v1, v80 dst_sel:DWORD dst_unused:UNUSED_PAD src0_sel:WORD_1
	s_cbranch_scc1 .LBB0_1233
	s_ashr_i32 s9, s36, 11
	s_ashr_i32 s8, s36, 3
	s_andn2_b32 s9, s9, 31
	v_add_u32_e32 v4, s9, v76
	s_lshl_b32 s9, s8, 7
	v_ashrrev_i32_e32 v5, 31, v4
	s_and_b32 s10, s9, 0xfff80
	s_ashr_i32 s9, s8, 31
	v_lshlrev_b64 v[4:5], 20, v[4:5]
	s_lshl_b64 s[38:39], s[8:9], 12
	v_lshl_add_u64 v[4:5], s[18:19], 0, v[4:5]
	s_add_u32 s40, s0, s38
	v_lshl_add_u64 v[4:5], v[4:5], 0, s[10:11]
	s_addc_u32 s41, s2, s39
	v_lshl_add_u64 v[4:5], v[4:5], 0, v[224:225]
	s_add_u32 s38, s28, s38
	global_load_dwordx2 v[6:7], v[4:5], off
	s_addc_u32 s39, s29, s39
	s_lshl_b64 s[8:9], s[8:9], 7
	v_lshl_add_u64 v[4:5], s[40:41], 0, v[78:79]
	s_add_u32 s8, s3, s8
	global_load_dwordx2 v[50:51], v[4:5], off
	v_lshl_add_u64 v[4:5], s[38:39], 0, v[78:79]
	s_addc_u32 s9, s7, s9
	global_load_dwordx2 v[62:63], v[4:5], off
	v_lshl_add_u64 v[4:5], v[76:77], 2, s[8:9]
	global_load_dword v52, v[4:5], off
	v_mov_b64_e32 v[16:17], v[40:41]
	v_mov_b64_e32 v[20:21], v[44:45]
	v_mov_b64_e32 v[18:19], v[42:43]
	v_mov_b64_e32 v[22:23], v[46:47]
	s_waitcnt vmcnt(3)
	v_cvt_f32_f16_e32 v4, v6
	v_cvt_f32_f16_sdwa v5, v6 dst_sel:DWORD dst_unused:UNUSED_PAD src0_sel:WORD_1
	v_cvt_f32_f16_e32 v6, v7
	v_cvt_f32_f16_sdwa v7, v7 dst_sel:DWORD dst_unused:UNUSED_PAD src0_sel:WORD_1
.LBB0_1233:
	s_lshl_b32 s37, s98, 1
	s_add_i32 s37, s37, s34
	s_cmp_lt_i32 s37, s99
	s_cselect_b64 s[8:9], -1, 0
	s_cmp_ge_i32 s37, s99
	s_cbranch_scc1 .LBB0_1235
	s_ashr_i32 s10, s37, 11
	s_andn2_b32 s10, s10, 31
	s_ashr_i32 s38, s37, 3
	v_add_u32_e32 v8, s10, v76
	v_ashrrev_i32_e32 v9, 31, v8
	s_lshl_b32 s10, s38, 7
	s_ashr_i32 s39, s38, 31
	v_lshlrev_b64 v[8:9], 20, v[8:9]
	s_and_b32 s10, s10, 0xfff80
	s_lshl_b64 s[40:41], s[38:39], 12
	v_lshl_add_u64 v[8:9], s[18:19], 0, v[8:9]
	s_add_u32 s42, s0, s40
	v_lshl_add_u64 v[8:9], v[8:9], 0, s[10:11]
	s_addc_u32 s43, s2, s41
	v_lshl_add_u64 v[8:9], v[8:9], 0, v[224:225]
	s_add_u32 s40, s28, s40
	global_load_dwordx2 v[8:9], v[8:9], off
	s_addc_u32 s41, s29, s41
	s_lshl_b64 s[38:39], s[38:39], 7
	v_lshl_add_u64 v[10:11], s[42:43], 0, v[78:79]
	s_add_u32 s38, s3, s38
	global_load_dwordx2 v[58:59], v[10:11], off
	v_lshl_add_u64 v[10:11], s[40:41], 0, v[78:79]
	s_addc_u32 s39, s7, s39
	global_load_dwordx2 v[64:65], v[10:11], off
	v_lshl_add_u64 v[10:11], v[76:77], 2, s[38:39]
	global_load_dword v56, v[10:11], off
	v_mov_b64_e32 v[32:33], v[40:41]
	v_mov_b64_e32 v[36:37], v[44:45]
	v_mov_b64_e32 v[34:35], v[42:43]
	v_mov_b64_e32 v[38:39], v[46:47]
	s_waitcnt vmcnt(3)
	v_cvt_f32_f16_sdwa v11, v9 dst_sel:DWORD dst_unused:UNUSED_PAD src0_sel:WORD_1
	v_cvt_f32_f16_e32 v10, v9
	v_cvt_f32_f16_sdwa v9, v8 dst_sel:DWORD dst_unused:UNUSED_PAD src0_sel:WORD_1
	v_cvt_f32_f16_e32 v8, v8
.LBB0_1235:
	s_mul_i32 s40, s98, 3
	s_add_i32 s40, s40, s34
	s_cmp_lt_i32 s40, s99
	s_cselect_b64 s[34:35], -1, 0
	s_cmp_ge_i32 s40, s99
	s_cbranch_scc1 .LBB0_1237
	s_ashr_i32 s10, s40, 11
	s_andn2_b32 s10, s10, 31
	s_ashr_i32 s38, s40, 3
	v_add_u32_e32 v12, s10, v76
	v_ashrrev_i32_e32 v13, 31, v12
	s_lshl_b32 s10, s38, 7
	s_ashr_i32 s39, s38, 31
	v_lshlrev_b64 v[12:13], 20, v[12:13]
	s_and_b32 s10, s10, 0xfff80
	s_lshl_b64 s[42:43], s[38:39], 12
	v_lshl_add_u64 v[12:13], s[18:19], 0, v[12:13]
	s_add_u32 s44, s0, s42
	v_lshl_add_u64 v[12:13], v[12:13], 0, s[10:11]
	s_addc_u32 s45, s2, s43
	v_lshl_add_u64 v[12:13], v[12:13], 0, v[224:225]
	s_add_u32 s42, s28, s42
	global_load_dwordx2 v[12:13], v[12:13], off
	s_addc_u32 s43, s29, s43
	s_lshl_b64 s[38:39], s[38:39], 7
	v_lshl_add_u64 v[14:15], s[44:45], 0, v[78:79]
	s_add_u32 s38, s3, s38
	global_load_dwordx2 v[60:61], v[14:15], off
	v_lshl_add_u64 v[14:15], s[42:43], 0, v[78:79]
	s_addc_u32 s39, s7, s39
	global_load_dwordx2 v[66:67], v[14:15], off
	v_lshl_add_u64 v[14:15], v[76:77], 2, s[38:39]
	global_load_dword v54, v[14:15], off
	v_mov_b64_e32 v[24:25], v[40:41]
	v_mov_b64_e32 v[28:29], v[44:45]
	v_mov_b64_e32 v[26:27], v[42:43]
	v_mov_b64_e32 v[30:31], v[46:47]
	s_waitcnt vmcnt(3)
	v_cvt_f32_f16_sdwa v15, v13 dst_sel:DWORD dst_unused:UNUSED_PAD src0_sel:WORD_1
	v_cvt_f32_f16_e32 v14, v13
	v_cvt_f32_f16_sdwa v13, v12 dst_sel:DWORD dst_unused:UNUSED_PAD src0_sel:WORD_1
	v_cvt_f32_f16_e32 v12, v12

.LBB0_1243:
	v_readlane_b32 s0, v253, 37
	v_readlane_b32 s20, v250, 0
	s_or_b32 s0, s0, 8
	v_readlane_b32 s23, v250, 3
	s_cmp_ge_i32 s0, s23
	s_mov_b64 s[72:73], 0
	v_readlane_b32 s21, v250, 1
	v_readlane_b32 s22, v250, 2
	s_cbranch_scc1 .LBB0_1299
	s_waitcnt vmcnt(0)
	v_readlane_b32 s2, v253, 40
	v_readlane_b32 s3, v253, 41
	s_and_b64 vcc, exec, s[2:3]
	s_waitcnt vmcnt(0)
	s_barrier
	s_cbranch_vccnz .LBB0_1298
	s_cmp_lg_u32 s101, 0
	s_cbranch_scc1 .Lmy_gchk_7
	s_mov_b32 s101, 2
	s_cmp_lg_u32 s94, 0x100
	s_cbranch_scc1 .Lmy_gchk_7
	v_readlane_b32 s8, v250, 0
	v_readlane_b32 s9, v250, 1
	s_mov_b32 s2, -1
	v_mbcnt_lo_u32_b32 v0, s2, 0
	v_mbcnt_hi_u32_b32 v0, s2, v0
	v_lshlrev_b32_e32 v0, 2, v0
	s_add_u32 s8, s8, 0x60000
	s_addc_u32 s9, s9, 0
	global_load_dword v1, v0, s[8:9] sc0 sc1
	global_load_dword v2, v0, s[8:9] offset:256 sc0 sc1
	global_load_dword v3, v0, s[8:9] offset:512 sc0 sc1
	global_load_dword v4, v0, s[8:9] offset:768 sc0 sc1
	v_and_b32_e32 v5, 28, v0
	global_load_dword v5, v5, s[8:9] sc0 sc1
	s_waitcnt vmcnt(0)
	v_cmp_eq_u32_e64 s[12:13], v1, v5
	s_nop 1
	v_cmp_ne_u32_e32 vcc, 0, v1
	v_cmp_eq_u32_e64 s[2:3], v1, v2
	s_and_b64 s[2:3], s[2:3], s[12:13]
	v_cmp_eq_u32_e64 s[12:13], v1, v3
	s_and_b64 s[2:3], s[2:3], vcc
	v_cmp_eq_u32_e64 s[8:9], v1, v4
	s_and_b64 s[2:3], s[2:3], s[12:13]
	s_and_b64 s[2:3], s[2:3], s[8:9]
	s_cmp_eq_u64 s[2:3], -1
	s_cbranch_scc0 .Lmy_gchk_7
	s_mov_b32 s101, 1
.Lmy_gchk_7:
	s_mov_b32 s0, -1
	s_nop 0
	v_mbcnt_lo_u32_b32 v0, s0, 0
	v_mbcnt_hi_u32_b32 v0, s0, v0
	s_nop 0
	v_cmp_eq_u32_e32 vcc, 0, v0
	s_and_saveexec_b64 s[18:19], vcc
	s_cbranch_execz .LBB0_1297
	s_cmp_lg_u32 s101, 1
	s_cbranch_scc1 .Lmy_gfull_7
	v_readlane_b32 s2, v253, 37
	v_readlane_b32 s3, v250, 7
	v_readlane_b32 s8, v250, 0
	v_readlane_b32 s9, v250, 1
	s_lshl_b32 s2, s2, 11
	s_add_i32 s2, s2, 0x7000
	s_and_b32 s3, s3, 63
	s_lshl_b32 s3, s3, 6
	s_add_i32 s2, s2, s3
	s_add_u32 s8, s8, 0x70000
	s_addc_u32 s9, s9, 0
	v_mov_b32_e32 v0, s2
	v_mov_b32_e32 v1, 1
	s_waitcnt vmcnt(0) lgkmcnt(0)
	global_atomic_add v0, v1, s[8:9]
	s_mov_b32 s2, 0

.Lmy_gdone_7:
	buffer_inv sc1
	s_waitcnt vmcnt(0)
	s_branch .LBB0_1297
.Lmy_gfull_7:
	v_readlane_b32 s0, v252, 30
	s_waitcnt vmcnt(0) expcnt(0) lgkmcnt(0)
	s_nop 0
	v_mov_b32_e32 v0, s0
	ds_read_b32 v2, v0
	v_readlane_b32 s0, v252, 31
	s_waitcnt lgkmcnt(0)
	v_cmp_ne_u32_e32 vcc, 0, v2
	v_mov_b32_e32 v0, s0
	ds_read_b32 v0, v0
	s_cbranch_vccnz .LBB0_1261
	v_readlane_b32 s8, v250, 4
	v_readlane_b32 s9, v250, 5
	s_load_dwordx2 s[2:3], s[8:9], 0x4
	s_waitcnt lgkmcnt(0)
	s_mul_i32 s0, s2, s94
	s_mul_i32 s0, s0, s3
	s_mov_b32 s2, 1
	s_branch .LBB0_1249
